# F13 + norm1 table build: first wait counted vmcnt(4) instead of vmcnt(0) (first consumer needs only the first of five table loads)
# baseline (speedup 1.0000x reference)
.LBB1_153:
	s_ashr_i32 s10, s5, 7
	s_mul_hi_i32 s11, s10, 0xc000
	s_mul_i32 s10, s10, 0xc000
	s_add_u32 s10, s2, s10
	s_addc_u32 s11, s3, s11
	v_lshl_add_u64 v[12:13], v[96:97], 2, s[10:11]
	s_barrier
	global_load_dwordx4 v[4:7], v[110:111], off
	global_load_dwordx4 v[8:11], v[114:115], off
	v_add_co_u32_e32 v16, vcc, s75, v12
	global_load_dwordx4 v[0:3], v[98:99], off
	s_nop 0
	v_addc_co_u32_e32 v17, vcc, 0, v13, vcc
	global_load_dwordx4 v[12:15], v[12:13], off
	s_nop 0
	global_load_dwordx4 v[16:19], v[16:17], off
	v_lshlrev_b32_e32 v173, 1, v102
	v_lshlrev_b32_e32 v172, 1, v104
	v_lshlrev_b32_e32 v171, 1, v106
	v_lshlrev_b32_e32 v112, 1, v108
	s_and_b64 vcc, exec, s[16:17]
	s_waitcnt vmcnt(4)
	v_pk_add_f32 v[6:7], v[6:7], 1.0 op_sel_hi:[1,0]
	v_pk_add_f32 v[4:5], v[4:5], 1.0 op_sel_hi:[1,0]
	s_waitcnt vmcnt(3)
	ds_write_b128 v170, v[8:11] offset:24576
	s_waitcnt vmcnt(2)
	v_pk_mul_f32 v[6:7], v[2:3], v[6:7]
	v_pk_mul_f32 v[4:5], v[0:1], v[4:5]
	ds_write_b128 v170, v[4:7] offset:16384
	s_waitcnt vmcnt(1)
	ds_write_b128 v170, v[12:15] offset:8192
	s_waitcnt vmcnt(0)
	v_pk_add_f32 v[4:5], v[18:19], 1.0 op_sel_hi:[1,0]
	v_pk_add_f32 v[6:7], v[16:17], 1.0 op_sel_hi:[1,0]
	v_pk_mul_f32 v[2:3], v[2:3], v[4:5]
	v_pk_mul_f32 v[0:1], v[0:1], v[6:7]
	ds_write_b128 v170, v[0:3]
	s_waitcnt lgkmcnt(0)
	s_barrier
	s_cbranch_vccz .LBB1_157
	s_lshl_b32 s10, s5, 5
	s_add_i32 s10, s10, s6
	s_ashr_i32 s11, s10, 31
	s_lshl_b64 s[36:37], s[10:11], 12
	v_lshl_add_u64 v[0:1], v[100:101], 0, s[36:37]
	global_load_dwordx4 v[52:55], v[0:1], off
	global_load_dwordx4 v[56:59], v[0:1], off offset:1024
	global_load_dwordx4 v[60:63], v[0:1], off offset:2048
	global_load_dwordx4 v[138:141], v[0:1], off offset:3072
	s_or_b32 s24, s10, 1
	s_or_b32 s26, s10, 2
	s_or_b32 s10, s10, 3
	s_ashr_i32 s25, s24, 31
	s_ashr_i32 s27, s26, 31
	s_ashr_i32 s11, s10, 31
	s_lshl_b64 s[38:39], s[24:25], 12
	s_lshl_b64 s[30:31], s[26:27], 12
	s_lshl_b64 s[26:27], s[10:11], 12
	v_lshl_add_u64 v[32:33], v[100:101], 0, s[38:39]
	v_lshl_add_u64 v[34:35], v[100:101], 0, s[30:31]
	ds_read_b128 v[4:7], v103
	ds_read_b128 v[0:3], v103 offset:4096
	ds_read_b128 v[12:15], v103 offset:8192
	ds_read_b128 v[8:11], v103 offset:12288
	ds_read_b128 v[20:23], v105
	ds_read_b128 v[16:19], v105 offset:4096
	ds_read_b128 v[28:31], v105 offset:8192
	ds_read_b128 v[24:27], v105 offset:12288
	v_lshl_add_u64 v[68:69], v[100:101], 0, s[26:27]
	global_load_dwordx4 v[146:149], v[32:33], off
	global_load_dwordx4 v[150:153], v[32:33], off offset:1024
	global_load_dwordx4 v[158:161], v[32:33], off offset:2048
	global_load_dwordx4 v[48:51], v[32:33], off offset:3072
	global_load_dwordx4 v[92:95], v[34:35], off
	global_load_dwordx4 v[84:87], v[34:35], off offset:1024
	global_load_dwordx4 v[76:79], v[34:35], off offset:2048
	global_load_dwordx4 v[64:67], v[34:35], off offset:3072
	global_load_dwordx4 v[44:47], v[68:69], off
	global_load_dwordx4 v[40:43], v[68:69], off offset:1024
	global_load_dwordx4 v[36:39], v[68:69], off offset:2048
	s_nop 0
	global_load_dwordx4 v[32:35], v[68:69], off offset:3072
	s_mov_b32 s10, 0x358637bd
	s_add_u32 s36, s29, s36
	s_addc_u32 s37, s8, s37
	s_add_u32 s38, s29, s38
	s_addc_u32 s39, s8, s39
	s_add_u32 s30, s29, s30
	s_addc_u32 s31, s8, s31
	s_add_u32 s26, s29, s26
	s_addc_u32 s27, s8, s27
	s_waitcnt vmcnt(15)
	v_lshlrev_b32_e32 v68, 16, v55
	v_and_b32_e32 v69, 0xffff0000, v55
	v_lshlrev_b32_e32 v70, 16, v53
	v_and_b32_e32 v71, 0xffff0000, v53
	v_lshlrev_b32_e32 v74, 16, v52
	v_and_b32_e32 v75, 0xffff0000, v52
	v_lshlrev_b32_e32 v72, 16, v54
	v_and_b32_e32 v73, 0xffff0000, v54
	s_waitcnt vmcnt(14)
	v_lshlrev_b32_e32 v80, 16, v59
	v_and_b32_e32 v81, 0xffff0000, v59
	v_lshlrev_b32_e32 v82, 16, v58
	v_and_b32_e32 v83, 0xffff0000, v58
	v_lshlrev_b32_e32 v88, 16, v57
	v_and_b32_e32 v89, 0xffff0000, v57
	v_lshlrev_b32_e32 v90, 16, v56
	v_and_b32_e32 v91, 0xffff0000, v56
	v_pk_mul_f32 v[52:53], v[68:69], v[68:69]
	v_pk_mul_f32 v[56:57], v[70:71], v[70:71]
	v_pk_mul_f32 v[58:59], v[74:75], v[74:75]
	v_pk_mul_f32 v[54:55], v[72:73], v[72:73]
	v_add_f32_e32 v52, v52, v53
	v_add_f32_e32 v53, v56, v57
	v_add_f32_e32 v56, v58, v59
	v_add_f32_e32 v53, v56, v53
	v_add_f32_e32 v54, v54, v55
	s_waitcnt vmcnt(12)
	v_lshlrev_b32_e32 v124, 16, v141
	v_and_b32_e32 v125, 0xffff0000, v141
	v_lshlrev_b32_e32 v130, 16, v140
	v_and_b32_e32 v131, 0xffff0000, v140
	v_pk_mul_f32 v[140:141], v[90:91], v[90:91]
	v_add_f32_e32 v53, v54, v53
	v_pk_mul_f32 v[120:121], v[88:89], v[88:89]
	v_add_f32_e32 v52, v52, v53
	v_add_f32_e32 v53, v140, v141
	v_lshlrev_b32_e32 v122, 16, v63
	v_and_b32_e32 v123, 0xffff0000, v63
	v_lshlrev_b32_e32 v126, 16, v62
	v_and_b32_e32 v127, 0xffff0000, v62
	v_pk_mul_f32 v[62:63], v[82:83], v[82:83]
	v_add_f32_e32 v52, v53, v52
	v_add_f32_e32 v53, v120, v121
	v_lshlrev_b32_e32 v128, 16, v61
	v_and_b32_e32 v129, 0xffff0000, v61
	v_lshlrev_b32_e32 v134, 16, v60
	v_and_b32_e32 v135, 0xffff0000, v60
	v_pk_mul_f32 v[60:61], v[80:81], v[80:81]
	v_add_f32_e32 v52, v53, v52
	v_add_f32_e32 v53, v62, v63
	v_pk_mul_f32 v[156:157], v[134:135], v[134:135]
	v_add_f32_e32 v52, v53, v52
	v_add_f32_e32 v53, v60, v61
	v_pk_mul_f32 v[154:155], v[128:129], v[128:129]
	v_add_f32_e32 v52, v53, v52
	v_add_f32_e32 v53, v156, v157
	v_pk_mul_f32 v[144:145], v[126:127], v[126:127]
	v_add_f32_e32 v52, v53, v52
	v_add_f32_e32 v53, v154, v155
	v_pk_mul_f32 v[142:143], v[122:123], v[122:123]
	v_lshlrev_b32_e32 v136, 16, v138
	v_and_b32_e32 v137, 0xffff0000, v138
	v_add_f32_e32 v52, v53, v52
	v_add_f32_e32 v53, v144, v145
	v_lshlrev_b32_e32 v132, 16, v139
	v_and_b32_e32 v133, 0xffff0000, v139
	v_pk_mul_f32 v[138:139], v[136:137], v[136:137]
	v_add_f32_e32 v52, v53, v52
	v_add_f32_e32 v53, v142, v143
	v_pk_mul_f32 v[166:167], v[132:133], v[132:133]
	v_add_f32_e32 v52, v53, v52
	v_add_f32_e32 v53, v138, v139
	v_pk_mul_f32 v[164:165], v[130:131], v[130:131]
	v_add_f32_e32 v52, v53, v52
	v_add_f32_e32 v53, v166, v167
	v_pk_mul_f32 v[162:163], v[124:125], v[124:125]
	v_add_f32_e32 v52, v53, v52
	v_add_f32_e32 v53, v164, v165
	v_add_f32_e32 v52, v53, v52
	v_add_f32_e32 v53, v162, v163
	v_add_f32_e32 v52, v53, v52
	s_waitcnt vmcnt(11)
	v_lshlrev_b32_e32 v138, 16, v149
	v_and_b32_e32 v139, 0xffff0000, v149
	v_add_f32_dpp v52, v52, v52 quad_perm:[1,0,3,2] row_mask:0xf bank_mask:0xf bound_ctrl:1
	v_lshlrev_b32_e32 v144, 16, v148
	v_and_b32_e32 v145, 0xffff0000, v148
	v_add_f32_dpp v52, v52, v52 quad_perm:[2,3,0,1] row_mask:0xf bank_mask:0xf bound_ctrl:1
	v_lshlrev_b32_e32 v148, 16, v147
	v_and_b32_e32 v149, 0xffff0000, v147
	v_add_f32_dpp v52, v52, v52 row_half_mirror row_mask:0xf bank_mask:0xf bound_ctrl:1
	v_lshlrev_b32_e32 v156, 16, v146
	v_and_b32_e32 v157, 0xffff0000, v146
	v_add_f32_dpp v52, v52, v52 row_mirror row_mask:0xf bank_mask:0xf bound_ctrl:1
	v_pk_mul_f32 v[60:61], v[148:149], v[148:149]
	v_pk_mul_f32 v[62:63], v[156:157], v[156:157]
	v_mov_b32_e32 v53, v52
	v_pk_mul_f32 v[58:59], v[144:145], v[144:145]
	v_add_f32_e32 v54, v60, v61
	v_add_f32_e32 v60, v62, v63
	v_permlane16_swap_b32_e32 v52, v53
	v_pk_mul_f32 v[56:57], v[138:139], v[138:139]
	s_waitcnt vmcnt(10)
	v_lshlrev_b32_e32 v164, 16, v150
	v_and_b32_e32 v165, 0xffff0000, v150
	v_add_f32_e32 v54, v60, v54
	v_add_f32_e32 v58, v58, v59
	v_add_f32_e32 v53, v52, v53
	v_lshlrev_b32_e32 v140, 16, v153
	v_and_b32_e32 v141, 0xffff0000, v153
	v_lshlrev_b32_e32 v146, 16, v152
	v_and_b32_e32 v147, 0xffff0000, v152
	v_lshlrev_b32_e32 v152, 16, v151
	v_and_b32_e32 v153, 0xffff0000, v151
	v_pk_mul_f32 v[178:179], v[164:165], v[164:165]
	v_add_f32_e32 v52, v56, v57
	v_add_f32_e32 v54, v58, v54
	v_pk_mul_f32 v[176:177], v[152:153], v[152:153]
	v_add_f32_e32 v52, v52, v54
	v_add_f32_e32 v54, v178, v179
	v_pk_mul_f32 v[174:175], v[146:147], v[146:147]
	v_add_f32_e32 v52, v54, v52
	v_add_f32_e32 v54, v176, v177
	v_pk_mul_f32 v[120:121], v[140:141], v[140:141]
	s_waitcnt vmcnt(9)
	v_lshlrev_b32_e32 v166, 16, v158
	v_and_b32_e32 v167, 0xffff0000, v158
	v_add_f32_e32 v52, v54, v52
	v_add_f32_e32 v54, v174, v175
	v_lshlrev_b32_e32 v142, 16, v161
	v_and_b32_e32 v143, 0xffff0000, v161
	v_lshlrev_b32_e32 v154, 16, v160
	v_and_b32_e32 v155, 0xffff0000, v160
	v_lshlrev_b32_e32 v160, 16, v159
	v_and_b32_e32 v161, 0xffff0000, v159
	v_pk_mul_f32 v[56:57], v[166:167], v[166:167]
	v_add_f32_e32 v52, v54, v52
	v_add_f32_e32 v54, v120, v121
	s_waitcnt vmcnt(8)
	v_lshlrev_b32_e32 v150, 16, v51
	v_and_b32_e32 v151, 0xffff0000, v51
	v_lshlrev_b32_e32 v158, 16, v50
	v_and_b32_e32 v159, 0xffff0000, v50
	v_pk_mul_f32 v[50:51], v[160:161], v[160:161]
	v_add_f32_e32 v52, v54, v52
	v_add_f32_e32 v54, v56, v57
	v_lshlrev_b32_e32 v162, 16, v49
	v_and_b32_e32 v163, 0xffff0000, v49
	v_lshlrev_b32_e32 v168, 16, v48
	v_and_b32_e32 v169, 0xffff0000, v48
	v_pk_mul_f32 v[48:49], v[154:155], v[154:155]
	v_add_f32_e32 v52, v54, v52
	v_add_f32_e32 v50, v50, v51
	v_pk_mul_f32 v[180:181], v[142:143], v[142:143]
	v_add_f32_e32 v50, v50, v52
	v_add_f32_e32 v48, v48, v49
	v_pk_mul_f32 v[176:177], v[168:169], v[168:169]
	v_add_f32_e32 v48, v48, v50
	v_add_f32_e32 v49, v180, v181
	v_pk_mul_f32 v[62:63], v[162:163], v[162:163]
	v_add_f32_e32 v48, v49, v48
	v_add_f32_e32 v49, v176, v177
	v_pk_mul_f32 v[58:59], v[158:159], v[158:159]
	v_add_f32_e32 v48, v49, v48
	v_add_f32_e32 v49, v62, v63
	v_pk_mul_f32 v[60:61], v[150:151], v[150:151]
	v_add_f32_e32 v48, v49, v48
	v_add_f32_e32 v49, v58, v59
	v_add_f32_e32 v48, v49, v48
	v_add_f32_e32 v49, v60, v61
	v_add_f32_e32 v48, v49, v48
	v_mov_b32_e32 v55, v53
	s_nop 1
	v_permlane32_swap_b32_e32 v53, v55
	v_add_f32_dpp v48, v48, v48 quad_perm:[1,0,3,2] row_mask:0xf bank_mask:0xf bound_ctrl:1
	v_mov_b64_e32 v[120:121], s[10:11]
	s_mov_b32 s10, 0x3a000000
	v_add_f32_dpp v48, v48, v48 quad_perm:[2,3,0,1] row_mask:0xf bank_mask:0xf bound_ctrl:1
	s_nop 1
	v_add_f32_dpp v48, v48, v48 row_half_mirror row_mask:0xf bank_mask:0xf bound_ctrl:1
	s_nop 1
	v_add_f32_dpp v48, v48, v48 row_mirror row_mask:0xf bank_mask:0xf bound_ctrl:1
	v_mov_b32_e32 v49, v48
	s_nop 1
	v_permlane16_swap_b32_e32 v48, v49
	v_add_f32_e32 v52, v48, v49
	v_mov_b32_e32 v54, v52
	s_nop 1
	v_permlane32_swap_b32_e32 v52, v54
	v_pk_add_f32 v[48:49], v[52:53], v[54:55]
	s_nop 0
	v_pk_fma_f32 v[178:179], v[48:49], s[10:11], v[120:121] op_sel_hi:[1,0,0]
	s_nop 0
	v_mul_f32_e32 v48, 0x4b800000, v179
	v_cmp_gt_f32_e32 vcc, s69, v179
	s_nop 1
	v_cndmask_b32_e32 v48, v179, v48, vcc
	v_rsq_f32_e32 v174, v48
	ds_read_b128 v[52:55], v107
	ds_read_b128 v[48:51], v107 offset:4096
	ds_read_b128 v[60:63], v107 offset:8192
	ds_read_b128 v[56:59], v107 offset:12288
	s_waitcnt vmcnt(0)
	v_and_b32_e32 v179, 0xffff0000, v33
	v_mul_f32_e32 v175, 0x45800000, v174
	v_cndmask_b32_e32 v180, v174, v175, vcc
	v_pk_mul_f32 v[74:75], v[180:181], v[74:75] op_sel_hi:[0,1]
	v_pk_mul_f32 v[72:73], v[180:181], v[72:73] op_sel_hi:[0,1]
	v_pk_mul_f32 v[70:71], v[180:181], v[70:71] op_sel_hi:[0,1]
	v_pk_mul_f32 v[68:69], v[180:181], v[68:69] op_sel_hi:[0,1]
	s_waitcnt lgkmcnt(9)
	v_pk_fma_f32 v[74:75], v[4:5], v[74:75], v[12:13]
	s_waitcnt lgkmcnt(8)
	v_pk_fma_f32 v[72:73], v[0:1], v[72:73], v[8:9]
	v_pk_fma_f32 v[70:71], v[6:7], v[70:71], v[14:15]
	v_pk_fma_f32 v[68:69], v[2:3], v[68:69], v[10:11]
	v_cvt_pk_bf16_f32 v174, v74, v75
	v_cvt_pk_bf16_f32 v175, v70, v71
	v_cvt_pk_bf16_f32 v176, v72, v73
	v_cvt_pk_bf16_f32 v177, v68, v69
	v_pk_mul_f32 v[90:91], v[180:181], v[90:91] op_sel_hi:[0,1]
	v_pk_mul_f32 v[82:83], v[180:181], v[82:83] op_sel_hi:[0,1]
	v_pk_mul_f32 v[88:89], v[180:181], v[88:89] op_sel_hi:[0,1]
	v_pk_mul_f32 v[80:81], v[180:181], v[80:81] op_sel_hi:[0,1]
	ds_read_b128 v[72:75], v109
	ds_read_b128 v[68:71], v109 offset:4096
	global_store_dwordx4 v173, v[174:177], s[36:37]
	s_waitcnt lgkmcnt(7)
	v_pk_fma_f32 v[90:91], v[20:21], v[90:91], v[28:29]
	s_waitcnt lgkmcnt(6)
	v_pk_fma_f32 v[82:83], v[16:17], v[82:83], v[24:25]
	v_pk_fma_f32 v[88:89], v[22:23], v[88:89], v[30:31]
	v_pk_fma_f32 v[80:81], v[18:19], v[80:81], v[26:27]
	v_cvt_pk_bf16_f32 v174, v90, v91
	v_cvt_pk_bf16_f32 v175, v88, v89
	v_cvt_pk_bf16_f32 v176, v82, v83
	v_cvt_pk_bf16_f32 v177, v80, v81
	ds_read_b128 v[88:91], v109 offset:8192
	ds_read_b128 v[80:83], v109 offset:12288
	v_pk_mul_f32 v[126:127], v[180:181], v[126:127] op_sel_hi:[0,1]
	global_store_dwordx4 v172, v[174:177], s[36:37]
	v_pk_mul_f32 v[134:135], v[180:181], v[134:135] op_sel_hi:[0,1]
	v_pk_mul_f32 v[122:123], v[180:181], v[122:123] op_sel_hi:[0,1]
	s_waitcnt lgkmcnt(4)
	v_pk_fma_f32 v[174:175], v[126:127], v[48:49], v[56:57]
	v_pk_mul_f32 v[126:127], v[180:181], v[128:129] op_sel_hi:[0,1]
	v_pk_fma_f32 v[134:135], v[134:135], v[52:53], v[60:61]
	v_pk_fma_f32 v[128:129], v[126:127], v[54:55], v[62:63]
	v_pk_fma_f32 v[122:123], v[122:123], v[50:51], v[58:59]
	v_cvt_pk_bf16_f32 v126, v134, v135
	v_cvt_pk_bf16_f32 v127, v128, v129
	v_cvt_pk_bf16_f32 v128, v174, v175
	v_cvt_pk_bf16_f32 v129, v122, v123
	v_pk_mul_f32 v[124:125], v[180:181], v[124:125] op_sel_hi:[0,1]
	global_store_dwordx4 v171, v[126:129], s[36:37]
	v_pk_mul_f32 v[122:123], v[180:181], v[136:137] op_sel_hi:[0,1]
	v_cmp_gt_f32_e32 vcc, s69, v178
	v_pk_mul_f32 v[126:127], v[180:181], v[130:131] op_sel_hi:[0,1]
	v_pk_mul_f32 v[128:129], v[180:181], v[132:133] op_sel_hi:[0,1]
	s_waitcnt lgkmcnt(0)
	v_pk_fma_f32 v[130:131], v[124:125], v[70:71], v[82:83]
	v_mul_f32_e32 v124, 0x4b800000, v178
	v_pk_fma_f32 v[122:123], v[122:123], v[72:73], v[88:89]
	v_pk_fma_f32 v[128:129], v[128:129], v[74:75], v[90:91]
	v_cndmask_b32_e32 v124, v178, v124, vcc
	v_cvt_pk_bf16_f32 v122, v122, v123
	v_cvt_pk_bf16_f32 v123, v128, v129
	v_rsq_f32_e32 v128, v124
	v_pk_fma_f32 v[126:127], v[126:127], v[68:69], v[80:81]
	v_cvt_pk_bf16_f32 v125, v130, v131
	v_cvt_pk_bf16_f32 v124, v126, v127
	global_store_dwordx4 v112, v[122:125], s[36:37]
	v_lshlrev_b32_e32 v132, 16, v92
	v_and_b32_e32 v133, 0xffff0000, v92
	v_mul_f32_e32 v122, 0x45800000, v128
	v_cndmask_b32_e32 v126, v128, v122, vcc
	v_pk_mul_f32 v[122:123], v[126:127], v[156:157] op_sel_hi:[0,1]
	v_pk_mul_f32 v[124:125], v[126:127], v[144:145] op_sel_hi:[0,1]
	v_pk_mul_f32 v[128:129], v[126:127], v[148:149] op_sel_hi:[0,1]
	v_pk_mul_f32 v[130:131], v[126:127], v[138:139] op_sel_hi:[0,1]
	v_pk_fma_f32 v[122:123], v[4:5], v[122:123], v[12:13]
	v_pk_fma_f32 v[124:125], v[0:1], v[124:125], v[8:9]
	v_pk_fma_f32 v[128:129], v[6:7], v[128:129], v[14:15]
	v_pk_fma_f32 v[130:131], v[2:3], v[130:131], v[10:11]
	v_cvt_pk_bf16_f32 v122, v122, v123
	v_cvt_pk_bf16_f32 v123, v128, v129
	v_cvt_pk_bf16_f32 v124, v124, v125
	v_cvt_pk_bf16_f32 v125, v130, v131
	global_store_dwordx4 v173, v[122:125], s[38:39]
	v_pk_mul_f32 v[128:129], v[126:127], v[152:153] op_sel_hi:[0,1]
	v_pk_mul_f32 v[130:131], v[126:127], v[140:141] op_sel_hi:[0,1]
	v_pk_mul_f32 v[122:123], v[126:127], v[164:165] op_sel_hi:[0,1]
	v_pk_mul_f32 v[124:125], v[126:127], v[146:147] op_sel_hi:[0,1]
	v_pk_fma_f32 v[122:123], v[20:21], v[122:123], v[28:29]
	v_pk_fma_f32 v[124:125], v[16:17], v[124:125], v[24:25]
	v_pk_fma_f32 v[128:129], v[22:23], v[128:129], v[30:31]
	v_pk_fma_f32 v[130:131], v[18:19], v[130:131], v[26:27]
	v_cvt_pk_bf16_f32 v122, v122, v123
	v_cvt_pk_bf16_f32 v123, v128, v129
	v_cvt_pk_bf16_f32 v124, v124, v125
	v_cvt_pk_bf16_f32 v125, v130, v131
	global_store_dwordx4 v172, v[122:125], s[38:39]
	v_pk_mul_f32 v[128:129], v[126:127], v[160:161] op_sel_hi:[0,1]
	v_pk_mul_f32 v[130:131], v[126:127], v[142:143] op_sel_hi:[0,1]
	v_pk_mul_f32 v[122:123], v[126:127], v[166:167] op_sel_hi:[0,1]
	v_pk_mul_f32 v[124:125], v[126:127], v[154:155] op_sel_hi:[0,1]
	v_pk_fma_f32 v[122:123], v[52:53], v[122:123], v[60:61]
	v_pk_fma_f32 v[124:125], v[48:49], v[124:125], v[56:57]
	v_pk_fma_f32 v[128:129], v[54:55], v[128:129], v[62:63]
	v_pk_fma_f32 v[130:131], v[50:51], v[130:131], v[58:59]
	v_cvt_pk_bf16_f32 v122, v122, v123
	v_cvt_pk_bf16_f32 v123, v128, v129
	v_cvt_pk_bf16_f32 v124, v124, v125
	v_cvt_pk_bf16_f32 v125, v130, v131
	global_store_dwordx4 v171, v[122:125], s[38:39]
	v_pk_mul_f32 v[128:129], v[126:127], v[162:163] op_sel_hi:[0,1]
	v_pk_fma_f32 v[128:129], v[74:75], v[128:129], v[90:91]
	v_pk_mul_f32 v[122:123], v[126:127], v[168:169] op_sel_hi:[0,1]
	v_pk_mul_f32 v[124:125], v[126:127], v[158:159] op_sel_hi:[0,1]
	v_pk_mul_f32 v[126:127], v[126:127], v[150:151] op_sel_hi:[0,1]
	v_pk_fma_f32 v[122:123], v[72:73], v[122:123], v[88:89]
	v_pk_fma_f32 v[124:125], v[68:69], v[124:125], v[80:81]
	v_pk_fma_f32 v[126:127], v[70:71], v[126:127], v[82:83]
	v_cvt_pk_bf16_f32 v122, v122, v123
	v_cvt_pk_bf16_f32 v123, v128, v129
	v_cvt_pk_bf16_f32 v124, v124, v125
	v_cvt_pk_bf16_f32 v125, v126, v127
	global_store_dwordx4 v112, v[122:125], s[38:39]
	v_lshlrev_b32_e32 v126, 16, v93
	v_and_b32_e32 v127, 0xffff0000, v93
	v_lshlrev_b32_e32 v122, 16, v95
	v_and_b32_e32 v123, 0xffff0000, v95
	v_pk_mul_f32 v[140:141], v[122:123], v[122:123]
	v_lshlrev_b32_e32 v124, 16, v94
	v_and_b32_e32 v125, 0xffff0000, v94
	v_pk_mul_f32 v[144:145], v[126:127], v[126:127]
	v_pk_mul_f32 v[146:147], v[132:133], v[132:133]
	v_pk_mul_f32 v[142:143], v[124:125], v[124:125]
	v_add_f32_e32 v140, v140, v141
	v_add_f32_e32 v141, v144, v145
	v_add_f32_e32 v144, v146, v147
	v_lshlrev_b32_e32 v134, 16, v84
	v_and_b32_e32 v135, 0xffff0000, v84
	v_add_f32_e32 v141, v144, v141
	v_add_f32_e32 v142, v142, v143
	v_lshlrev_b32_e32 v128, 16, v85
	v_and_b32_e32 v129, 0xffff0000, v85
	v_pk_mul_f32 v[154:155], v[134:135], v[134:135]
	v_add_f32_e32 v141, v142, v141
	v_lshlrev_b32_e32 v94, 16, v86
	v_and_b32_e32 v95, 0xffff0000, v86
	v_pk_mul_f32 v[152:153], v[128:129], v[128:129]
	v_add_f32_e32 v140, v140, v141
	v_add_f32_e32 v141, v154, v155
	v_lshlrev_b32_e32 v92, 16, v87
	v_and_b32_e32 v93, 0xffff0000, v87
	v_pk_mul_f32 v[150:151], v[94:95], v[94:95]
	v_add_f32_e32 v140, v141, v140
	v_add_f32_e32 v141, v152, v153
	v_pk_mul_f32 v[148:149], v[92:93], v[92:93]
	v_lshlrev_b32_e32 v136, 16, v76
	v_and_b32_e32 v137, 0xffff0000, v76
	v_add_f32_e32 v140, v141, v140
	v_add_f32_e32 v141, v150, v151
	v_lshlrev_b32_e32 v130, 16, v77
	v_and_b32_e32 v131, 0xffff0000, v77
	v_pk_mul_f32 v[162:163], v[136:137], v[136:137]
	v_add_f32_e32 v140, v141, v140
	v_add_f32_e32 v141, v148, v149
	v_lshlrev_b32_e32 v86, 16, v78
	v_and_b32_e32 v87, 0xffff0000, v78
	v_pk_mul_f32 v[160:161], v[130:131], v[130:131]
	v_add_f32_e32 v140, v141, v140
	v_add_f32_e32 v141, v162, v163
	v_lshlrev_b32_e32 v84, 16, v79
	v_and_b32_e32 v85, 0xffff0000, v79
	v_pk_mul_f32 v[158:159], v[86:87], v[86:87]
	v_add_f32_e32 v140, v141, v140
	v_add_f32_e32 v141, v160, v161
	v_pk_mul_f32 v[156:157], v[84:85], v[84:85]
	v_lshlrev_b32_e32 v138, 16, v64
	v_and_b32_e32 v139, 0xffff0000, v64
	v_add_f32_e32 v140, v141, v140
	v_add_f32_e32 v141, v158, v159
	v_lshlrev_b32_e32 v76, 16, v67
	v_and_b32_e32 v77, 0xffff0000, v67
	v_lshlrev_b32_e32 v78, 16, v66
	v_and_b32_e32 v79, 0xffff0000, v66
	v_lshlrev_b32_e32 v66, 16, v65
	v_and_b32_e32 v67, 0xffff0000, v65
	v_pk_mul_f32 v[64:65], v[138:139], v[138:139]
	v_add_f32_e32 v140, v141, v140
	v_add_f32_e32 v141, v156, v157
	v_pk_mul_f32 v[168:169], v[66:67], v[66:67]
	v_add_f32_e32 v140, v141, v140
	v_add_f32_e32 v64, v64, v65
	v_pk_mul_f32 v[166:167], v[78:79], v[78:79]
	v_add_f32_e32 v64, v64, v140
	v_add_f32_e32 v65, v168, v169
	v_pk_mul_f32 v[164:165], v[76:77], v[76:77]
	v_add_f32_e32 v64, v65, v64
	v_add_f32_e32 v65, v166, v167
	v_add_f32_e32 v64, v65, v64
	v_add_f32_e32 v65, v164, v165
	v_add_f32_e32 v64, v65, v64
	v_lshlrev_b32_e32 v148, 16, v45
	v_and_b32_e32 v149, 0xffff0000, v45
	v_add_f32_dpp v64, v64, v64 quad_perm:[1,0,3,2] row_mask:0xf bank_mask:0xf bound_ctrl:1
	v_lshlrev_b32_e32 v152, 16, v44
	v_and_b32_e32 v153, 0xffff0000, v44
	v_add_f32_dpp v64, v64, v64 quad_perm:[2,3,0,1] row_mask:0xf bank_mask:0xf bound_ctrl:1
	v_lshlrev_b32_e32 v146, 16, v46
	v_and_b32_e32 v147, 0xffff0000, v46
	v_add_f32_dpp v64, v64, v64 row_half_mirror row_mask:0xf bank_mask:0xf bound_ctrl:1
	v_pk_mul_f32 v[150:151], v[148:149], v[148:149]
	v_pk_mul_f32 v[154:155], v[152:153], v[152:153]
	v_add_f32_dpp v64, v64, v64 row_mirror row_mask:0xf bank_mask:0xf bound_ctrl:1
	v_mov_b32_e32 v65, v64
	s_nop 1
	v_permlane16_swap_b32_e32 v64, v65
	v_add_f32_e32 v141, v64, v65
	v_lshlrev_b32_e32 v64, 16, v47
	v_and_b32_e32 v65, 0xffff0000, v47
	v_pk_mul_f32 v[46:47], v[146:147], v[146:147]
	v_add_f32_e32 v142, v150, v151
	v_add_f32_e32 v150, v154, v155
	v_pk_mul_f32 v[144:145], v[64:65], v[64:65]
	v_lshlrev_b32_e32 v164, 16, v40
	v_and_b32_e32 v165, 0xffff0000, v40
	v_add_f32_e32 v142, v150, v142
	v_add_f32_e32 v46, v46, v47
	v_lshlrev_b32_e32 v160, 16, v41
	v_and_b32_e32 v161, 0xffff0000, v41
	v_pk_mul_f32 v[40:41], v[164:165], v[164:165]
	v_add_f32_e32 v140, v144, v145
	v_add_f32_e32 v142, v46, v142
	v_lshlrev_b32_e32 v158, 16, v42
	v_and_b32_e32 v159, 0xffff0000, v42
	v_pk_mul_f32 v[162:163], v[160:161], v[160:161]
	v_add_f32_e32 v140, v140, v142
	v_add_f32_e32 v142, v40, v41
	v_lshlrev_b32_e32 v44, 16, v43
	v_and_b32_e32 v45, 0xffff0000, v43
	v_pk_mul_f32 v[42:43], v[158:159], v[158:159]
	v_add_f32_e32 v140, v142, v140
	v_add_f32_e32 v142, v162, v163
	v_pk_mul_f32 v[156:157], v[44:45], v[44:45]
	v_lshlrev_b32_e32 v174, 16, v36
	v_and_b32_e32 v175, 0xffff0000, v36
	v_add_f32_e32 v140, v142, v140
	v_add_f32_e32 v142, v42, v43
	v_lshlrev_b32_e32 v166, 16, v39
	v_and_b32_e32 v167, 0xffff0000, v39
	v_lshlrev_b32_e32 v168, 16, v38
	v_and_b32_e32 v169, 0xffff0000, v38
	v_lshlrev_b32_e32 v38, 16, v37
	v_and_b32_e32 v39, 0xffff0000, v37
	v_pk_mul_f32 v[150:151], v[174:175], v[174:175]
	v_add_f32_e32 v140, v142, v140
	v_add_f32_e32 v142, v156, v157
	v_pk_mul_f32 v[144:145], v[38:39], v[38:39]
	v_add_f32_e32 v140, v142, v140
	v_add_f32_e32 v142, v150, v151
	v_lshlrev_b32_e32 v36, 16, v35
	v_and_b32_e32 v37, 0xffff0000, v35
	v_lshlrev_b32_e32 v176, 16, v34
	v_and_b32_e32 v177, 0xffff0000, v34
	v_pk_mul_f32 v[34:35], v[168:169], v[168:169]
	v_add_f32_e32 v140, v142, v140
	v_add_f32_e32 v142, v144, v145
	v_lshlrev_b32_e32 v178, 16, v33
	v_lshlrev_b32_e32 v180, 16, v32
	v_and_b32_e32 v181, 0xffff0000, v32
	v_pk_mul_f32 v[32:33], v[166:167], v[166:167]
	v_add_f32_e32 v140, v142, v140
	v_add_f32_e32 v34, v34, v35
	v_pk_mul_f32 v[42:43], v[180:181], v[180:181]
	v_add_f32_e32 v34, v34, v140
	v_add_f32_e32 v32, v32, v33
	v_pk_mul_f32 v[154:155], v[178:179], v[178:179]
	v_add_f32_e32 v32, v32, v34
	v_add_f32_e32 v33, v42, v43
	v_pk_mul_f32 v[40:41], v[176:177], v[176:177]
	v_add_f32_e32 v32, v33, v32
	v_add_f32_e32 v33, v154, v155
	v_pk_mul_f32 v[46:47], v[36:37], v[36:37]
	v_add_f32_e32 v32, v33, v32
	v_add_f32_e32 v33, v40, v41
	v_add_f32_e32 v32, v33, v32
	v_add_f32_e32 v33, v46, v47
	v_add_f32_e32 v32, v33, v32
	v_mov_b32_e32 v143, v141
	s_nop 1
	v_permlane32_swap_b32_e32 v141, v143
	v_add_f32_dpp v32, v32, v32 quad_perm:[1,0,3,2] row_mask:0xf bank_mask:0xf bound_ctrl:1
	s_nop 1
	v_add_f32_dpp v32, v32, v32 quad_perm:[2,3,0,1] row_mask:0xf bank_mask:0xf bound_ctrl:1
	s_nop 1
	v_add_f32_dpp v32, v32, v32 row_half_mirror row_mask:0xf bank_mask:0xf bound_ctrl:1
	s_nop 1
	v_add_f32_dpp v32, v32, v32 row_mirror row_mask:0xf bank_mask:0xf bound_ctrl:1
	v_mov_b32_e32 v33, v32
	s_nop 1
	v_permlane16_swap_b32_e32 v32, v33
	v_add_f32_e32 v140, v32, v33
	v_mov_b32_e32 v142, v140
	s_nop 1
	v_permlane32_swap_b32_e32 v140, v142
	v_pk_add_f32 v[32:33], v[140:141], v[142:143]
	s_nop 0
	v_pk_fma_f32 v[40:41], v[32:33], s[10:11], v[120:121] op_sel_hi:[1,0,0]
	s_nop 0
	v_mul_f32_e32 v32, 0x4b800000, v41
	v_cmp_gt_f32_e32 vcc, s69, v41
	s_nop 1
	v_cndmask_b32_e32 v32, v41, v32, vcc
	v_rsq_f32_e32 v32, v32
	v_mul_f32_e32 v41, 0x4b800000, v40
	v_mul_f32_e32 v33, 0x45800000, v32
	v_cndmask_b32_e32 v42, v32, v33, vcc
	v_pk_mul_f32 v[32:33], v[42:43], v[132:133] op_sel_hi:[0,1]
	v_pk_mul_f32 v[34:35], v[42:43], v[124:125] op_sel_hi:[0,1]
	v_pk_mul_f32 v[46:47], v[42:43], v[126:127] op_sel_hi:[0,1]
	v_pk_mul_f32 v[120:121], v[42:43], v[122:123] op_sel_hi:[0,1]
	v_pk_fma_f32 v[32:33], v[4:5], v[32:33], v[12:13]
	v_pk_fma_f32 v[34:35], v[0:1], v[34:35], v[8:9]
	v_pk_fma_f32 v[46:47], v[6:7], v[46:47], v[14:15]
	v_pk_fma_f32 v[120:121], v[2:3], v[120:121], v[10:11]
	v_cvt_pk_bf16_f32 v32, v32, v33
	v_cvt_pk_bf16_f32 v33, v46, v47
	v_cvt_pk_bf16_f32 v34, v34, v35
	v_cvt_pk_bf16_f32 v35, v120, v121
	global_store_dwordx4 v173, v[32:35], s[30:31]
	v_pk_mul_f32 v[46:47], v[42:43], v[128:129] op_sel_hi:[0,1]
	v_pk_mul_f32 v[92:93], v[42:43], v[92:93] op_sel_hi:[0,1]
	v_pk_mul_f32 v[32:33], v[42:43], v[134:135] op_sel_hi:[0,1]
	v_pk_mul_f32 v[34:35], v[42:43], v[94:95] op_sel_hi:[0,1]
	v_pk_fma_f32 v[32:33], v[20:21], v[32:33], v[28:29]
	v_pk_fma_f32 v[34:35], v[16:17], v[34:35], v[24:25]
	v_pk_fma_f32 v[46:47], v[22:23], v[46:47], v[30:31]
	v_pk_fma_f32 v[92:93], v[18:19], v[92:93], v[26:27]
	v_cvt_pk_bf16_f32 v32, v32, v33
	v_cvt_pk_bf16_f32 v33, v46, v47
	v_cvt_pk_bf16_f32 v34, v34, v35
	v_cvt_pk_bf16_f32 v35, v92, v93
	global_store_dwordx4 v172, v[32:35], s[30:31]
	v_pk_mul_f32 v[46:47], v[42:43], v[130:131] op_sel_hi:[0,1]
	v_pk_mul_f32 v[84:85], v[42:43], v[84:85] op_sel_hi:[0,1]
	v_pk_mul_f32 v[32:33], v[42:43], v[136:137] op_sel_hi:[0,1]
	v_pk_mul_f32 v[34:35], v[42:43], v[86:87] op_sel_hi:[0,1]
	v_cmp_gt_f32_e32 vcc, s69, v40
	v_pk_fma_f32 v[32:33], v[52:53], v[32:33], v[60:61]
	v_pk_fma_f32 v[34:35], v[48:49], v[34:35], v[56:57]
	v_pk_fma_f32 v[46:47], v[54:55], v[46:47], v[62:63]
	v_pk_fma_f32 v[84:85], v[50:51], v[84:85], v[58:59]
	v_cndmask_b32_e32 v40, v40, v41, vcc
	v_cvt_pk_bf16_f32 v32, v32, v33
	v_cvt_pk_bf16_f32 v33, v46, v47
	v_cvt_pk_bf16_f32 v34, v34, v35
	v_cvt_pk_bf16_f32 v35, v84, v85
	v_rsq_f32_e32 v40, v40
	global_store_dwordx4 v171, v[32:35], s[30:31]
	v_pk_mul_f32 v[46:47], v[42:43], v[66:67] op_sel_hi:[0,1]
	v_pk_fma_f32 v[46:47], v[74:75], v[46:47], v[90:91]
	v_pk_mul_f32 v[32:33], v[42:43], v[138:139] op_sel_hi:[0,1]
	v_pk_mul_f32 v[34:35], v[42:43], v[78:79] op_sel_hi:[0,1]
	v_pk_mul_f32 v[42:43], v[42:43], v[76:77] op_sel_hi:[0,1]
	v_pk_fma_f32 v[32:33], v[72:73], v[32:33], v[88:89]
	v_pk_fma_f32 v[34:35], v[68:69], v[34:35], v[80:81]
	v_pk_fma_f32 v[42:43], v[70:71], v[42:43], v[82:83]
	v_cvt_pk_bf16_f32 v32, v32, v33
	v_cvt_pk_bf16_f32 v33, v46, v47
	v_cvt_pk_bf16_f32 v34, v34, v35
	v_cvt_pk_bf16_f32 v35, v42, v43
	global_store_dwordx4 v112, v[32:35], s[30:31]
	s_nop 1
	v_mul_f32_e32 v32, 0x45800000, v40
	v_cndmask_b32_e32 v32, v40, v32, vcc
	v_pk_mul_f32 v[34:35], v[32:33], v[152:153] op_sel_hi:[0,1]
	v_pk_fma_f32 v[4:5], v[4:5], v[34:35], v[12:13]
	v_pk_mul_f32 v[12:13], v[32:33], v[146:147] op_sel_hi:[0,1]
	v_pk_fma_f32 v[8:9], v[0:1], v[12:13], v[8:9]
	v_pk_mul_f32 v[0:1], v[32:33], v[148:149] op_sel_hi:[0,1]
	v_pk_fma_f32 v[6:7], v[6:7], v[0:1], v[14:15]
	v_pk_mul_f32 v[0:1], v[32:33], v[64:65] op_sel_hi:[0,1]
	v_pk_fma_f32 v[10:11], v[2:3], v[0:1], v[10:11]
	v_cvt_pk_bf16_f32 v0, v4, v5
	v_cvt_pk_bf16_f32 v1, v6, v7
	v_cvt_pk_bf16_f32 v2, v8, v9
	v_cvt_pk_bf16_f32 v3, v10, v11
	global_store_dwordx4 v173, v[0:3], s[26:27]
	v_pk_mul_f32 v[4:5], v[32:33], v[160:161] op_sel_hi:[0,1]
	v_pk_mul_f32 v[6:7], v[32:33], v[44:45] op_sel_hi:[0,1]
	v_pk_mul_f32 v[0:1], v[32:33], v[164:165] op_sel_hi:[0,1]
	v_pk_mul_f32 v[2:3], v[32:33], v[158:159] op_sel_hi:[0,1]
	v_pk_fma_f32 v[0:1], v[20:21], v[0:1], v[28:29]
	v_pk_fma_f32 v[2:3], v[16:17], v[2:3], v[24:25]
	v_pk_fma_f32 v[4:5], v[22:23], v[4:5], v[30:31]
	v_pk_fma_f32 v[6:7], v[18:19], v[6:7], v[26:27]
	v_cvt_pk_bf16_f32 v0, v0, v1
	v_cvt_pk_bf16_f32 v1, v4, v5
	v_cvt_pk_bf16_f32 v2, v2, v3
	v_cvt_pk_bf16_f32 v3, v6, v7
	global_store_dwordx4 v172, v[0:3], s[26:27]
	v_pk_mul_f32 v[4:5], v[32:33], v[38:39] op_sel_hi:[0,1]
	v_pk_mul_f32 v[6:7], v[32:33], v[166:167] op_sel_hi:[0,1]
	v_pk_mul_f32 v[0:1], v[32:33], v[174:175] op_sel_hi:[0,1]
	v_pk_mul_f32 v[2:3], v[32:33], v[168:169] op_sel_hi:[0,1]
	v_pk_fma_f32 v[0:1], v[52:53], v[0:1], v[60:61]
	v_pk_fma_f32 v[2:3], v[48:49], v[2:3], v[56:57]
	v_pk_fma_f32 v[4:5], v[54:55], v[4:5], v[62:63]
	v_pk_fma_f32 v[6:7], v[50:51], v[6:7], v[58:59]
	v_cvt_pk_bf16_f32 v0, v0, v1
	v_cvt_pk_bf16_f32 v1, v4, v5
	v_cvt_pk_bf16_f32 v2, v2, v3
	v_cvt_pk_bf16_f32 v3, v6, v7
	global_store_dwordx4 v171, v[0:3], s[26:27]
	v_pk_mul_f32 v[4:5], v[32:33], v[178:179] op_sel_hi:[0,1]
	v_pk_mul_f32 v[6:7], v[32:33], v[36:37] op_sel_hi:[0,1]
	v_pk_mul_f32 v[0:1], v[32:33], v[180:181] op_sel_hi:[0,1]
	v_pk_mul_f32 v[2:3], v[32:33], v[176:177] op_sel_hi:[0,1]
	v_pk_fma_f32 v[0:1], v[72:73], v[0:1], v[88:89]
	v_pk_fma_f32 v[2:3], v[68:69], v[2:3], v[80:81]
	v_pk_fma_f32 v[4:5], v[74:75], v[4:5], v[90:91]
	v_pk_fma_f32 v[6:7], v[70:71], v[6:7], v[82:83]
	v_cvt_pk_bf16_f32 v0, v0, v1
	v_cvt_pk_bf16_f32 v1, v4, v5
	v_cvt_pk_bf16_f32 v2, v2, v3
	v_cvt_pk_bf16_f32 v3, v6, v7
	s_andn2_b64 vcc, exec, s[18:19]
	global_store_dwordx4 v112, v[0:3], s[26:27]
	s_cbranch_vccnz .LBB1_156
	s_lshl_b32 s10, s5, 1
	s_add_i32 s10, s10, s7
	s_ashr_i32 s11, s10, 31
	s_lshl_b64 s[10:11], s[10:11], 12
	v_lshl_add_u64 v[12:13], v[100:101], 0, s[10:11]
	global_load_dwordx4 v[0:3], v[12:13], off
	global_load_dwordx4 v[4:7], v[12:13], off offset:1024
	global_load_dwordx4 v[8:11], v[12:13], off offset:2048
	s_nop 0
	global_load_dwordx4 v[12:15], v[12:13], off offset:3072
	ds_read_b128 v[16:19], v103 offset:16384
	ds_read_b128 v[20:23], v103 offset:20480
	ds_read_b128 v[24:27], v103 offset:24576
	ds_read_b128 v[28:31], v103 offset:28672
	ds_read_b128 v[32:35], v105 offset:16384
	ds_read_b128 v[36:39], v105 offset:20480
	ds_read_b128 v[40:43], v105 offset:24576
	ds_read_b128 v[44:47], v105 offset:28672
	ds_read_b128 v[48:51], v107 offset:16384
	ds_read_b128 v[52:55], v107 offset:20480
	ds_read_b128 v[56:59], v107 offset:24576
	ds_read_b128 v[60:63], v107 offset:28672
	s_add_u32 s26, s29, s10
	s_addc_u32 s27, s8, s11
	s_waitcnt vmcnt(3)
	v_lshlrev_b32_e32 v64, 16, v3
	v_and_b32_e32 v65, 0xffff0000, v3
	v_lshlrev_b32_e32 v68, 16, v1
	v_and_b32_e32 v69, 0xffff0000, v1
	v_lshlrev_b32_e32 v70, 16, v0
	v_and_b32_e32 v71, 0xffff0000, v0
	v_lshlrev_b32_e32 v66, 16, v2
	v_and_b32_e32 v67, 0xffff0000, v2
	s_waitcnt vmcnt(2)
	v_lshlrev_b32_e32 v72, 16, v7
	v_and_b32_e32 v73, 0xffff0000, v7
	v_lshlrev_b32_e32 v74, 16, v6
	v_and_b32_e32 v75, 0xffff0000, v6
	v_lshlrev_b32_e32 v76, 16, v5
	v_and_b32_e32 v77, 0xffff0000, v5
	v_lshlrev_b32_e32 v78, 16, v4
	v_and_b32_e32 v79, 0xffff0000, v4
	v_pk_mul_f32 v[0:1], v[64:65], v[64:65]
	v_pk_mul_f32 v[4:5], v[68:69], v[68:69]
	v_pk_mul_f32 v[6:7], v[70:71], v[70:71]
	v_pk_mul_f32 v[2:3], v[66:67], v[66:67]
	v_add_f32_e32 v0, v0, v1
	v_add_f32_e32 v1, v4, v5
	v_add_f32_e32 v4, v6, v7
	v_add_f32_e32 v2, v2, v3
	v_add_f32_e32 v1, v4, v1
	s_waitcnt vmcnt(0)
	v_lshlrev_b32_e32 v88, 16, v15
	v_and_b32_e32 v89, 0xffff0000, v15
	v_lshlrev_b32_e32 v90, 16, v14
	v_and_b32_e32 v91, 0xffff0000, v14
	v_pk_mul_f32 v[14:15], v[78:79], v[78:79]
	v_add_f32_e32 v1, v2, v1
	v_lshlrev_b32_e32 v92, 16, v13
	v_and_b32_e32 v93, 0xffff0000, v13
	v_lshlrev_b32_e32 v94, 16, v12
	v_and_b32_e32 v95, 0xffff0000, v12
	v_pk_mul_f32 v[12:13], v[76:77], v[76:77]
	v_add_f32_e32 v3, v14, v15
	v_add_f32_e32 v0, v0, v1
	v_lshlrev_b32_e32 v80, 16, v11
	v_and_b32_e32 v81, 0xffff0000, v11
	v_lshlrev_b32_e32 v82, 16, v10
	v_and_b32_e32 v83, 0xffff0000, v10
	v_pk_mul_f32 v[10:11], v[74:75], v[74:75]
	v_add_f32_e32 v5, v12, v13
	v_add_f32_e32 v0, v3, v0
	v_lshlrev_b32_e32 v84, 16, v9
	v_and_b32_e32 v85, 0xffff0000, v9
	v_lshlrev_b32_e32 v86, 16, v8
	v_and_b32_e32 v87, 0xffff0000, v8
	v_pk_mul_f32 v[8:9], v[72:73], v[72:73]
	v_add_f32_e32 v6, v10, v11
	v_add_f32_e32 v0, v5, v0
	v_pk_mul_f32 v[126:127], v[86:87], v[86:87]
	v_add_f32_e32 v7, v8, v9
	v_add_f32_e32 v0, v6, v0
	v_pk_mul_f32 v[124:125], v[84:85], v[84:85]
	v_add_f32_e32 v8, v126, v127
	v_add_f32_e32 v0, v7, v0
	v_pk_mul_f32 v[122:123], v[82:83], v[82:83]
	v_add_f32_e32 v9, v124, v125
	v_add_f32_e32 v0, v8, v0
	v_pk_mul_f32 v[120:121], v[80:81], v[80:81]
	v_add_f32_e32 v10, v122, v123
	v_add_f32_e32 v0, v9, v0
	v_pk_mul_f32 v[134:135], v[94:95], v[94:95]
	v_add_f32_e32 v11, v120, v121
	v_add_f32_e32 v0, v10, v0
	v_pk_mul_f32 v[132:133], v[92:93], v[92:93]
	v_add_f32_e32 v12, v134, v135
	v_add_f32_e32 v0, v11, v0
	v_pk_mul_f32 v[130:131], v[90:91], v[90:91]
	v_add_f32_e32 v13, v132, v133
	v_add_f32_e32 v0, v12, v0
	v_pk_mul_f32 v[128:129], v[88:89], v[88:89]
	v_add_f32_e32 v14, v130, v131
	v_add_f32_e32 v0, v13, v0
	v_add_f32_e32 v15, v128, v129
	v_add_f32_e32 v0, v14, v0
	v_add_f32_e32 v0, v15, v0
	s_nop 1
	v_add_f32_dpp v0, v0, v0 quad_perm:[1,0,3,2] row_mask:0xf bank_mask:0xf bound_ctrl:1
	s_nop 1
	v_add_f32_dpp v0, v0, v0 quad_perm:[2,3,0,1] row_mask:0xf bank_mask:0xf bound_ctrl:1
	s_nop 1
	v_add_f32_dpp v0, v0, v0 row_half_mirror row_mask:0xf bank_mask:0xf bound_ctrl:1
	s_nop 1
	v_add_f32_dpp v0, v0, v0 row_mirror row_mask:0xf bank_mask:0xf bound_ctrl:1
	v_mov_b32_e32 v1, v0
	s_nop 1
	v_permlane16_swap_b32_e32 v0, v1
	v_add_f32_e32 v0, v0, v1
	v_mov_b32_e32 v1, v0
	s_nop 1
	v_permlane32_swap_b32_e32 v0, v1
	v_add_f32_e32 v0, v0, v1
	v_fmamk_f32 v0, v0, 0x3a000000, v214
	v_mul_f32_e32 v1, 0x4b800000, v0
	v_cmp_gt_f32_e32 vcc, s69, v0
	s_nop 1
	v_cndmask_b32_e32 v0, v0, v1, vcc
	v_rsq_f32_e32 v120, v0
	ds_read_b128 v[0:3], v109 offset:16384
	ds_read_b128 v[4:7], v109 offset:20480
	ds_read_b128 v[8:11], v109 offset:24576
	ds_read_b128 v[12:15], v109 offset:28672
	v_mul_f32_e32 v121, 0x45800000, v120
	v_cndmask_b32_e32 v120, v120, v121, vcc
	v_pk_mul_f32 v[70:71], v[120:121], v[70:71] op_sel_hi:[0,1]
	s_waitcnt lgkmcnt(13)
	v_pk_fma_f32 v[16:17], v[16:17], v[70:71], v[24:25]
	v_pk_mul_f32 v[24:25], v[120:121], v[66:67] op_sel_hi:[0,1]
	s_waitcnt lgkmcnt(12)
	v_pk_fma_f32 v[20:21], v[20:21], v[24:25], v[28:29]
	v_pk_mul_f32 v[24:25], v[120:121], v[68:69] op_sel_hi:[0,1]
	v_pk_fma_f32 v[18:19], v[18:19], v[24:25], v[26:27]
	v_pk_mul_f32 v[24:25], v[120:121], v[64:65] op_sel_hi:[0,1]
	v_pk_fma_f32 v[22:23], v[22:23], v[24:25], v[30:31]
	v_cvt_pk_bf16_f32 v16, v16, v17
	v_cvt_pk_bf16_f32 v17, v18, v19
	v_cvt_pk_bf16_f32 v18, v20, v21
	v_cvt_pk_bf16_f32 v19, v22, v23
	global_store_dwordx4 v173, v[16:19], s[26:27]
	v_pk_mul_f32 v[20:21], v[120:121], v[76:77] op_sel_hi:[0,1]
	v_pk_mul_f32 v[22:23], v[120:121], v[72:73] op_sel_hi:[0,1]
	v_pk_mul_f32 v[16:17], v[120:121], v[78:79] op_sel_hi:[0,1]
	v_pk_mul_f32 v[18:19], v[120:121], v[74:75] op_sel_hi:[0,1]
	s_waitcnt lgkmcnt(9)
	v_pk_fma_f32 v[16:17], v[32:33], v[16:17], v[40:41]
	s_waitcnt lgkmcnt(8)
	v_pk_fma_f32 v[18:19], v[36:37], v[18:19], v[44:45]
	v_pk_fma_f32 v[20:21], v[34:35], v[20:21], v[42:43]
	v_pk_fma_f32 v[22:23], v[38:39], v[22:23], v[46:47]
	v_cvt_pk_bf16_f32 v16, v16, v17
	v_cvt_pk_bf16_f32 v17, v20, v21
	v_cvt_pk_bf16_f32 v18, v18, v19
	v_cvt_pk_bf16_f32 v19, v22, v23
	global_store_dwordx4 v172, v[16:19], s[26:27]
	v_pk_mul_f32 v[20:21], v[120:121], v[84:85] op_sel_hi:[0,1]
	v_pk_mul_f32 v[22:23], v[120:121], v[80:81] op_sel_hi:[0,1]
	v_pk_mul_f32 v[16:17], v[120:121], v[86:87] op_sel_hi:[0,1]
	v_pk_mul_f32 v[18:19], v[120:121], v[82:83] op_sel_hi:[0,1]
	s_waitcnt lgkmcnt(5)
	v_pk_fma_f32 v[16:17], v[16:17], v[48:49], v[56:57]
	s_waitcnt lgkmcnt(4)
	v_pk_fma_f32 v[18:19], v[18:19], v[52:53], v[60:61]
	v_pk_fma_f32 v[20:21], v[20:21], v[50:51], v[58:59]
	v_pk_fma_f32 v[22:23], v[22:23], v[54:55], v[62:63]
	v_cvt_pk_bf16_f32 v16, v16, v17
	v_cvt_pk_bf16_f32 v17, v20, v21
	v_cvt_pk_bf16_f32 v18, v18, v19
	v_cvt_pk_bf16_f32 v19, v22, v23
	global_store_dwordx4 v171, v[16:19], s[26:27]
	s_nop 1
	v_pk_mul_f32 v[16:17], v[120:121], v[94:95] op_sel_hi:[0,1]
	s_waitcnt lgkmcnt(1)
	v_pk_fma_f32 v[0:1], v[16:17], v[0:1], v[8:9]
	v_pk_mul_f32 v[8:9], v[120:121], v[90:91] op_sel_hi:[0,1]
	s_waitcnt lgkmcnt(0)
	v_pk_fma_f32 v[4:5], v[8:9], v[4:5], v[12:13]
	v_pk_mul_f32 v[8:9], v[120:121], v[92:93] op_sel_hi:[0,1]
	v_pk_fma_f32 v[2:3], v[8:9], v[2:3], v[10:11]
	v_pk_mul_f32 v[8:9], v[120:121], v[88:89] op_sel_hi:[0,1]
	v_pk_fma_f32 v[6:7], v[8:9], v[6:7], v[14:15]
	v_cvt_pk_bf16_f32 v0, v0, v1
	v_cvt_pk_bf16_f32 v1, v2, v3
	v_cvt_pk_bf16_f32 v2, v4, v5
	v_cvt_pk_bf16_f32 v3, v6, v7
	global_store_dwordx4 v112, v[0:3], s[26:27]
